# speedup vs baseline: 1.0061x; 1.0061x over previous
.LBB0_292:
	s_or_b64 exec, exec, s[0:1]
	v_or_b32_e32 v0, s92, v160
	v_ashrrev_i32_e32 v1, 31, v0
	v_lshlrev_b64 v[0:1], 2, v[0:1]
	v_lshl_add_u64 v[144:145], s[70:71], 0, v[0:1]
	s_waitcnt lgkmcnt(0)
	s_barrier
	v_lshl_add_u64 v[142:143], s[60:61], 0, v[0:1]
	global_load_dwordx4 v[170:173], v[144:145], off
	global_load_dwordx4 v[174:177], v[142:143], off
	global_load_dwordx4 v[186:189], v[144:145], off offset:64
	global_load_dwordx4 v[190:193], v[142:143], off offset:64
	global_load_dwordx4 v[202:205], v[144:145], off offset:512
	global_load_dwordx4 v[206:209], v[142:143], off offset:512
	global_load_dwordx4 v[218:221], v[144:145], off offset:576
	global_load_dwordx4 v[222:225], v[142:143], off offset:576
	v_lshlrev_b32_e32 v164, 3, v157
	ds_read_b64 v[8:9], v164 offset:8192
	s_cmp_lg_u64 s[98:99], 0
	s_cselect_b64 s[0:1], -1, 0
	v_lshl_or_b32 v146, v160, 1, v156
	s_and_b64 vcc, exec, s[0:1]
	s_waitcnt lgkmcnt(0)
	v_pk_add_f32 v[10:11], v[124:125], v[8:9] op_sel_hi:[1,0] neg_lo:[0,1] neg_hi:[0,1]
	v_pk_add_f32 v[124:125], v[126:127], v[8:9] op_sel_hi:[1,0] neg_lo:[0,1] neg_hi:[0,1]
	v_pk_mul_f32 v[10:11], v[8:9], v[10:11] op_sel:[1,0]
	v_pk_mul_f32 v[124:125], v[8:9], v[124:125] op_sel:[1,0]
	s_waitcnt vmcnt(0)
	v_mov_b32_e32 v4, v174
	v_mov_b32_e32 v5, v175
	v_mov_b32_e32 v6, v176
	v_mov_b32_e32 v7, v177
	v_mov_b32_e32 v0, v170
	v_mov_b32_e32 v1, v171
	v_mov_b32_e32 v2, v172
	v_mov_b32_e32 v3, v173
	v_pk_fma_f32 v[8:9], v[0:1], v[10:11], v[4:5]
	v_pk_fma_f32 v[10:11], v[2:3], v[124:125], v[6:7]
	s_cbranch_vccz .LBB0_318
	v_mad_u64_u32 v[126:127], s[2:3], v157, s48, v[146:147]
	v_cvt_pk_bf16_f32 v124, v8, v9
	v_cvt_pk_bf16_f32 v125, v10, v11
	ds_write_b64 v126, v[124:125]
	v_lshlrev_b32_e32 v124, 2, v160
	s_cbranch_execnz .LBB0_295

.LBB0_304:
	ds_read_b64 v[8:9], v164 offset:8192
	v_or_b32_e32 v77, 16, v160
	s_and_b64 vcc, exec, s[4:5]
	v_lshl_or_b32 v76, v77, 1, v156
	s_waitcnt lgkmcnt(0)
	v_pk_add_f32 v[10:11], v[120:121], v[8:9] op_sel_hi:[1,0] neg_lo:[0,1] neg_hi:[0,1]
	v_pk_add_f32 v[78:79], v[122:123], v[8:9] op_sel_hi:[1,0] neg_lo:[0,1] neg_hi:[0,1]
	v_pk_mul_f32 v[10:11], v[8:9], v[10:11] op_sel:[1,0]
	v_pk_mul_f32 v[78:79], v[8:9], v[78:79] op_sel:[1,0]
	s_nop 1
	v_mov_b32_e32 v4, v190
	v_mov_b32_e32 v5, v191
	v_mov_b32_e32 v6, v192
	v_mov_b32_e32 v7, v193
	v_mov_b32_e32 v0, v186
	v_mov_b32_e32 v1, v187
	v_mov_b32_e32 v2, v188
	v_mov_b32_e32 v3, v189
	v_pk_fma_f32 v[8:9], v[0:1], v[10:11], v[4:5]
	v_pk_fma_f32 v[10:11], v[2:3], v[78:79], v[6:7]
	s_cbranch_vccnz .LBB0_322
	v_mad_u64_u32 v[92:93], s[2:3], v157, s48, v[76:77]
	v_cvt_pk_bf16_f32 v78, v8, v9
	v_cvt_pk_bf16_f32 v79, v10, v11
	ds_write_b64 v92, v[78:79]
	v_lshlrev_b32_e32 v78, 2, v77
	s_cbranch_execnz .LBB0_307

.LBB0_329:
	s_barrier
	ds_read_b64 v[8:9], v164 offset:8192
	s_and_b64 vcc, exec, s[4:5]
	s_waitcnt lgkmcnt(0)
	v_pk_add_f32 v[10:11], v[116:117], v[8:9] op_sel_hi:[1,0] neg_lo:[0,1] neg_hi:[0,1]
	v_pk_add_f32 v[104:105], v[118:119], v[8:9] op_sel_hi:[1,0] neg_lo:[0,1] neg_hi:[0,1]
	v_pk_mul_f32 v[10:11], v[8:9], v[10:11] op_sel:[1,0]
	v_pk_mul_f32 v[104:105], v[8:9], v[104:105] op_sel:[1,0]
	s_nop 1
	v_mov_b32_e32 v4, v206
	v_mov_b32_e32 v5, v207
	v_mov_b32_e32 v6, v208
	v_mov_b32_e32 v7, v209
	v_mov_b32_e32 v0, v202
	v_mov_b32_e32 v1, v203
	v_mov_b32_e32 v2, v204
	v_mov_b32_e32 v3, v205
	v_pk_fma_f32 v[8:9], v[0:1], v[10:11], v[4:5]
	v_pk_fma_f32 v[10:11], v[2:3], v[104:105], v[6:7]
	s_cbranch_vccnz .LBB0_382
	v_mad_u64_u32 v[106:107], s[0:1], v157, s48, v[146:147]
	v_cvt_pk_bf16_f32 v104, v8, v9
	v_cvt_pk_bf16_f32 v105, v10, v11
	ds_write_b64 v106, v[104:105]
	s_cbranch_execnz .LBB0_332

.LBB0_341:
	ds_read_b64 v[8:9], v164 offset:8192
	s_and_b64 vcc, exec, s[4:5]
	s_waitcnt lgkmcnt(0)
	v_pk_add_f32 v[10:11], v[112:113], v[8:9] op_sel_hi:[1,0] neg_lo:[0,1] neg_hi:[0,1]
	v_pk_add_f32 v[68:69], v[114:115], v[8:9] op_sel_hi:[1,0] neg_lo:[0,1] neg_hi:[0,1]
	v_pk_mul_f32 v[10:11], v[8:9], v[10:11] op_sel:[1,0]
	v_pk_mul_f32 v[68:69], v[8:9], v[68:69] op_sel:[1,0]
	s_nop 1
	v_mov_b32_e32 v4, v222
	v_mov_b32_e32 v5, v223
	v_mov_b32_e32 v6, v224
	v_mov_b32_e32 v7, v225
	v_mov_b32_e32 v0, v218
	v_mov_b32_e32 v1, v219
	v_mov_b32_e32 v2, v220
	v_mov_b32_e32 v3, v221
	v_pk_fma_f32 v[8:9], v[0:1], v[10:11], v[4:5]
	v_pk_fma_f32 v[10:11], v[2:3], v[68:69], v[6:7]
	s_cbranch_vccnz .LBB0_386
	v_mad_u64_u32 v[70:71], s[0:1], v157, s48, v[76:77]
	v_cvt_pk_bf16_f32 v68, v8, v9
	v_cvt_pk_bf16_f32 v69, v10, v11
	ds_write_b64 v70, v[68:69]
	s_cbranch_execnz .LBB0_344

.LBB0_356:
	s_barrier
	ds_read_b64 v[8:9], v164 offset:9216
	s_and_b64 vcc, exec, s[4:5]
	s_waitcnt lgkmcnt(0)
	v_pk_add_f32 v[10:11], v[60:61], v[8:9] op_sel_hi:[1,0] neg_lo:[0,1] neg_hi:[0,1]
	v_pk_add_f32 v[60:61], v[62:63], v[8:9] op_sel_hi:[1,0] neg_lo:[0,1] neg_hi:[0,1]
	v_pk_mul_f32 v[10:11], v[8:9], v[10:11] op_sel:[1,0]
	v_pk_mul_f32 v[60:61], v[8:9], v[60:61] op_sel:[1,0]
	s_nop 1
	v_mov_b32_e32 v4, v174
	v_mov_b32_e32 v5, v175
	v_mov_b32_e32 v6, v176
	v_mov_b32_e32 v7, v177
	v_mov_b32_e32 v0, v170
	v_mov_b32_e32 v1, v171
	v_mov_b32_e32 v2, v172
	v_mov_b32_e32 v3, v173
	v_pk_fma_f32 v[8:9], v[0:1], v[10:11], v[4:5]
	v_pk_fma_f32 v[10:11], v[2:3], v[60:61], v[6:7]
	s_cbranch_vccnz .LBB0_391
	v_mad_u64_u32 v[62:63], s[0:1], v157, s48, v[146:147]
	v_cvt_pk_bf16_f32 v60, v8, v9
	v_cvt_pk_bf16_f32 v61, v10, v11
	ds_write_b64 v62, v[60:61]
	s_cbranch_execnz .LBB0_359

.LBB0_368:
	ds_read_b64 v[8:9], v164 offset:9216
	s_and_b64 vcc, exec, s[4:5]
	s_waitcnt lgkmcnt(0)
	v_pk_add_f32 v[10:11], v[56:57], v[8:9] op_sel_hi:[1,0] neg_lo:[0,1] neg_hi:[0,1]
	v_pk_add_f32 v[44:45], v[58:59], v[8:9] op_sel_hi:[1,0] neg_lo:[0,1] neg_hi:[0,1]
	v_pk_mul_f32 v[10:11], v[8:9], v[10:11] op_sel:[1,0]
	v_pk_mul_f32 v[44:45], v[8:9], v[44:45] op_sel:[1,0]
	s_nop 1
	v_mov_b32_e32 v4, v190
	v_mov_b32_e32 v5, v191
	v_mov_b32_e32 v6, v192
	v_mov_b32_e32 v7, v193
	v_mov_b32_e32 v0, v186
	v_mov_b32_e32 v1, v187
	v_mov_b32_e32 v2, v188
	v_mov_b32_e32 v3, v189
	v_pk_fma_f32 v[8:9], v[0:1], v[10:11], v[4:5]
	v_pk_fma_f32 v[10:11], v[2:3], v[44:45], v[6:7]
	s_cbranch_vccnz .LBB0_395
	v_mad_u64_u32 v[46:47], s[0:1], v157, s48, v[76:77]
	v_cvt_pk_bf16_f32 v44, v8, v9
	v_cvt_pk_bf16_f32 v45, v10, v11
	ds_write_b64 v46, v[44:45]
	s_cbranch_execnz .LBB0_371

.LBB0_402:
	s_barrier
	ds_read_b64 v[8:9], v164 offset:9216
	s_and_b64 vcc, exec, s[4:5]
	s_waitcnt lgkmcnt(0)
	v_pk_add_f32 v[10:11], v[52:53], v[8:9] op_sel_hi:[1,0] neg_lo:[0,1] neg_hi:[0,1]
	v_pk_add_f32 v[52:53], v[54:55], v[8:9] op_sel_hi:[1,0] neg_lo:[0,1] neg_hi:[0,1]
	v_pk_mul_f32 v[10:11], v[8:9], v[10:11] op_sel:[1,0]
	v_pk_mul_f32 v[52:53], v[8:9], v[52:53] op_sel:[1,0]
	s_nop 1
	v_mov_b32_e32 v4, v206
	v_mov_b32_e32 v5, v207
	v_mov_b32_e32 v6, v208
	v_mov_b32_e32 v7, v209
	v_mov_b32_e32 v0, v202
	v_mov_b32_e32 v1, v203
	v_mov_b32_e32 v2, v204
	v_mov_b32_e32 v3, v205
	v_pk_fma_f32 v[8:9], v[0:1], v[10:11], v[4:5]
	v_pk_fma_f32 v[10:11], v[2:3], v[52:53], v[6:7]
	s_cbranch_vccnz .LBB0_436
	v_mad_u64_u32 v[54:55], s[0:1], v157, s48, v[146:147]
	v_cvt_pk_bf16_f32 v52, v8, v9
	v_cvt_pk_bf16_f32 v53, v10, v11
	ds_write_b64 v54, v[52:53]
	s_cbranch_execnz .LBB0_405

.LBB0_414:
	ds_read_b64 v[8:9], v164 offset:9216
	s_and_b64 vcc, exec, s[4:5]
	s_waitcnt lgkmcnt(0)
	v_pk_add_f32 v[10:11], v[48:49], v[8:9] op_sel_hi:[1,0] neg_lo:[0,1] neg_hi:[0,1]
	v_pk_add_f32 v[20:21], v[50:51], v[8:9] op_sel_hi:[1,0] neg_lo:[0,1] neg_hi:[0,1]
	v_pk_mul_f32 v[10:11], v[8:9], v[10:11] op_sel:[1,0]
	v_pk_mul_f32 v[20:21], v[8:9], v[20:21] op_sel:[1,0]
	s_nop 1
	v_mov_b32_e32 v4, v222
	v_mov_b32_e32 v5, v223
	v_mov_b32_e32 v6, v224
	v_mov_b32_e32 v7, v225
	v_mov_b32_e32 v0, v218
	v_mov_b32_e32 v1, v219
	v_mov_b32_e32 v2, v220
	v_mov_b32_e32 v3, v221
	v_pk_fma_f32 v[8:9], v[0:1], v[10:11], v[4:5]
	v_pk_fma_f32 v[10:11], v[2:3], v[20:21], v[6:7]
	s_cbranch_vccnz .LBB0_440
	v_mad_u64_u32 v[22:23], s[0:1], v157, s48, v[76:77]
	v_cvt_pk_bf16_f32 v20, v8, v9
	v_cvt_pk_bf16_f32 v21, v10, v11
	ds_write_b64 v22, v[20:21]
	s_cbranch_execnz .LBB0_417
